# speedup vs baseline: 1.0047x; 1.0040x over previous
.LBB0_166:
.LBB0_167:
.LBB0_169:
	ds_read_b128 v[66:69], v225
	ds_read_b128 v[70:73], v226
	ds_read_b128 v[74:77], v227
	ds_read_b128 v[78:81], v228
	ds_read_b128 v[212:215], v225 offset:8192
	ds_read_b128 v[250:253], v226 offset:8192
	s_add_i32 s8, s98, 0xffffff40
	s_cmp_le_i32 s8, s74
	s_waitcnt lgkmcnt(5)
	v_mfma_f32_32x32x16_bf16 v[82:97], v[66:69], v[98:101], 0
	s_waitcnt lgkmcnt(4)
	v_mfma_f32_32x32x16_bf16 v[82:97], v[70:73], v[102:105], v[82:97]
	s_waitcnt lgkmcnt(3)
	v_mfma_f32_32x32x16_bf16 v[82:97], v[74:77], v[106:109], v[82:97]
	s_waitcnt lgkmcnt(2)
	v_mfma_f32_32x32x16_bf16 v[82:97], v[78:81], v[110:113], v[82:97]
	s_waitcnt lgkmcnt(1)
	v_mfma_f32_32x32x16_bf16 v[66:81], v[212:215], v[98:101], 0
	ds_read_b128 v[212:215], v227 offset:8192
	s_waitcnt lgkmcnt(1)
	v_mfma_f32_32x32x16_bf16 v[66:81], v[250:253], v[102:105], v[66:81]
	ds_read_b128 v[250:253], v228 offset:8192
	s_waitcnt lgkmcnt(1)
	v_mfma_f32_32x32x16_bf16 v[66:81], v[212:215], v[106:109], v[66:81]
	s_waitcnt lgkmcnt(0)
	v_mfma_f32_32x32x16_bf16 v[66:81], v[250:253], v[110:113], v[66:81]
	s_cbranch_scc1 .LBB0_171
	v_cmp_gt_i32_e64 s[68:69], 26, v231
	v_cmp_gt_i32_e64 s[70:71], 27, v231
	v_cmp_gt_i32_e64 s[66:67], 25, v231
	s_and_b64 s[68:69], s[70:71], s[68:69]
	v_cmp_gt_i32_e64 s[64:65], 24, v231
	s_and_b64 s[66:67], s[68:69], s[66:67]
	v_cmp_gt_i32_e64 s[62:63], 19, v231
	s_and_b64 s[64:65], s[66:67], s[64:65]
	v_cmp_gt_i32_e64 s[60:61], 18, v231
	s_and_b64 s[62:63], s[64:65], s[62:63]
	v_cmp_gt_i32_e64 s[58:59], 17, v231
	s_and_b64 s[60:61], s[62:63], s[60:61]
	v_cmp_gt_i32_e64 s[56:57], 16, v231
	s_and_b64 s[58:59], s[60:61], s[58:59]
	v_cmp_gt_i32_e64 s[54:55], 11, v231
	s_and_b64 s[56:57], s[58:59], s[56:57]
	v_cmp_gt_i32_e64 s[52:53], 10, v231
	s_and_b64 s[54:55], s[56:57], s[54:55]
	v_cmp_gt_i32_e64 s[50:51], 9, v231
	s_and_b64 s[52:53], s[54:55], s[52:53]
	v_cmp_gt_i32_e64 s[48:49], 8, v231
	s_and_b64 s[50:51], s[52:53], s[50:51]
	v_cmp_gt_i32_e64 s[46:47], 3, v231
	s_and_b64 s[48:49], s[50:51], s[48:49]
	v_cmp_gt_i32_e64 s[44:45], 2, v231
	s_and_b64 s[46:47], s[48:49], s[46:47]
	v_cmp_gt_i32_e64 s[42:43], 1, v231
	s_and_b64 s[44:45], s[46:47], s[44:45]
	v_cmp_gt_i32_e64 s[40:41], 0, v231
	s_and_b64 s[42:43], s[44:45], s[42:43]
	s_and_b64 s[40:41], s[42:43], s[40:41]
	v_cmp_gt_i32_e64 s[36:37], 58, v231
	v_cndmask_b32_e64 v82, v82, v210, s[40:41]
	v_cmp_gt_i32_e64 s[40:41], 59, v231
	v_cmp_gt_i32_e64 s[34:35], 57, v231
	s_and_b64 s[36:37], s[40:41], s[36:37]
	v_cmp_gt_i32_e64 s[30:31], 56, v231
	s_and_b64 s[34:35], s[36:37], s[34:35]
	v_cmp_gt_i32_e64 s[28:29], 51, v231
	s_and_b64 s[30:31], s[34:35], s[30:31]
	v_cmp_gt_i32_e64 s[26:27], 50, v231
	s_and_b64 s[28:29], s[30:31], s[28:29]
	v_cmp_gt_i32_e64 s[24:25], 49, v231
	s_and_b64 s[26:27], s[28:29], s[26:27]
	v_cmp_gt_i32_e64 s[22:23], 48, v231
	s_and_b64 s[24:25], s[26:27], s[24:25]
	v_cmp_gt_i32_e64 s[20:21], 43, v231
	s_and_b64 s[22:23], s[24:25], s[22:23]
	v_cmp_gt_i32_e64 s[18:19], 42, v231
	s_and_b64 s[20:21], s[22:23], s[20:21]
	v_cmp_gt_i32_e64 s[16:17], 41, v231
	s_and_b64 s[18:19], s[20:21], s[18:19]
	v_cmp_gt_i32_e64 s[14:15], 40, v231
	s_and_b64 s[16:17], s[18:19], s[16:17]
	v_cmp_gt_i32_e64 s[12:13], 35, v231
	s_and_b64 s[14:15], s[16:17], s[14:15]
	v_cmp_gt_i32_e64 s[10:11], 34, v231
	s_and_b64 s[12:13], s[14:15], s[12:13]
	v_cmp_gt_i32_e64 s[8:9], 33, v231
	s_and_b64 s[10:11], s[12:13], s[10:11]
	v_cmp_gt_i32_e32 vcc, 32, v231
	s_and_b64 s[8:9], s[10:11], s[8:9]
	s_and_b64 vcc, s[8:9], vcc
	v_cndmask_b32_e64 v97, v97, v210, s[70:71]
	v_cndmask_b32_e64 v96, v96, v210, s[68:69]
	v_cndmask_b32_e64 v95, v95, v210, s[66:67]
	v_cndmask_b32_e64 v94, v94, v210, s[64:65]
	v_cndmask_b32_e64 v93, v93, v210, s[62:63]
	v_cndmask_b32_e64 v92, v92, v210, s[60:61]
	v_cndmask_b32_e64 v91, v91, v210, s[58:59]
	v_cndmask_b32_e64 v90, v90, v210, s[56:57]
	v_cndmask_b32_e64 v89, v89, v210, s[54:55]
	v_cndmask_b32_e64 v88, v88, v210, s[52:53]
	v_cndmask_b32_e64 v87, v87, v210, s[50:51]
	v_cndmask_b32_e64 v86, v86, v210, s[48:49]
	v_cndmask_b32_e64 v85, v85, v210, s[46:47]
	v_cndmask_b32_e64 v84, v84, v210, s[44:45]
	v_cndmask_b32_e64 v83, v83, v210, s[42:43]
	v_cndmask_b32_e64 v81, v81, v210, s[40:41]
	v_cndmask_b32_e64 v80, v80, v210, s[36:37]
	v_cndmask_b32_e64 v79, v79, v210, s[34:35]
	v_cndmask_b32_e64 v78, v78, v210, s[30:31]
	v_cndmask_b32_e64 v77, v77, v210, s[28:29]
	v_cndmask_b32_e64 v76, v76, v210, s[26:27]
	v_cndmask_b32_e64 v75, v75, v210, s[24:25]
	v_cndmask_b32_e64 v74, v74, v210, s[22:23]
	v_cndmask_b32_e64 v73, v73, v210, s[20:21]
	v_cndmask_b32_e64 v72, v72, v210, s[18:19]
	v_cndmask_b32_e64 v71, v71, v210, s[16:17]
	v_cndmask_b32_e64 v70, v70, v210, s[14:15]
	v_cndmask_b32_e64 v69, v69, v210, s[12:13]
	v_cndmask_b32_e64 v68, v68, v210, s[10:11]
	v_cndmask_b32_e64 v67, v67, v210, s[8:9]
	v_cndmask_b32_e32 v66, v66, v210, vcc

.LBB0_175:
	v_cndmask_b32_e64 v233, v234, v233, s[8:9]
	v_mul_f32_e32 v206, 0xbe38aa3b, v233
	v_fmamk_f32 v82, v82, 0x3e38aa3b, v206
	v_fmamk_f32 v83, v83, 0x3e38aa3b, v206
	v_fmamk_f32 v84, v84, 0x3e38aa3b, v206
	v_fmamk_f32 v85, v85, 0x3e38aa3b, v206
	v_fmamk_f32 v86, v86, 0x3e38aa3b, v206
	v_fmamk_f32 v87, v87, 0x3e38aa3b, v206
	v_fmamk_f32 v88, v88, 0x3e38aa3b, v206
	v_fmamk_f32 v89, v89, 0x3e38aa3b, v206
	v_fmamk_f32 v90, v90, 0x3e38aa3b, v206
	v_fmamk_f32 v91, v91, 0x3e38aa3b, v206
	v_fmamk_f32 v92, v92, 0x3e38aa3b, v206
	v_fmamk_f32 v93, v93, 0x3e38aa3b, v206
	v_fmamk_f32 v94, v94, 0x3e38aa3b, v206
	v_fmamk_f32 v95, v95, 0x3e38aa3b, v206
	v_fmamk_f32 v96, v96, 0x3e38aa3b, v206
	v_fmamk_f32 v97, v97, 0x3e38aa3b, v206
	v_fmamk_f32 v66, v66, 0x3e38aa3b, v206
	v_fmamk_f32 v67, v67, 0x3e38aa3b, v206
	v_fmamk_f32 v68, v68, 0x3e38aa3b, v206
	v_fmamk_f32 v69, v69, 0x3e38aa3b, v206
	v_fmamk_f32 v70, v70, 0x3e38aa3b, v206
	v_fmamk_f32 v71, v71, 0x3e38aa3b, v206
	v_fmamk_f32 v72, v72, 0x3e38aa3b, v206
	v_fmamk_f32 v73, v73, 0x3e38aa3b, v206
	v_fmamk_f32 v74, v74, 0x3e38aa3b, v206
	v_fmamk_f32 v75, v75, 0x3e38aa3b, v206
	v_fmamk_f32 v76, v76, 0x3e38aa3b, v206
	v_fmamk_f32 v77, v77, 0x3e38aa3b, v206
	v_fmamk_f32 v78, v78, 0x3e38aa3b, v206
	v_fmamk_f32 v79, v79, 0x3e38aa3b, v206
	v_fmamk_f32 v80, v80, 0x3e38aa3b, v206
	v_fmac_f32_e32 v206, 0x3e38aa3b, v81
	v_exp_f32_e32 v81, v82
	v_exp_f32_e32 v82, v83
	v_exp_f32_e32 v83, v84
	v_exp_f32_e32 v84, v85
	v_exp_f32_e32 v85, v86
	v_exp_f32_e32 v86, v87
	v_exp_f32_e32 v87, v88
	v_exp_f32_e32 v88, v89
	v_exp_f32_e32 v89, v90
	v_exp_f32_e32 v90, v91
	v_exp_f32_e32 v91, v92
	v_exp_f32_e32 v92, v93
	v_exp_f32_e32 v93, v94
	v_exp_f32_e32 v94, v95
	v_exp_f32_e32 v95, v96
	v_exp_f32_e32 v96, v97
	v_exp_f32_e32 v97, v66
	v_add_f32_e32 v66, 0, v81
	v_add_f32_e32 v66, v82, v66
	v_add_f32_e32 v66, v83, v66
	v_add_f32_e32 v66, v84, v66
	v_add_f32_e32 v66, v85, v66
	v_add_f32_e32 v66, v86, v66
	v_add_f32_e32 v66, v87, v66
	v_add_f32_e32 v66, v88, v66
	v_add_f32_e32 v66, v89, v66
	v_add_f32_e32 v66, v90, v66
	v_add_f32_e32 v66, v91, v66
	v_add_f32_e32 v66, v92, v66
	v_add_f32_e32 v66, v93, v66
	v_exp_f32_e32 v212, v67
	v_add_f32_e32 v66, v94, v66
	v_exp_f32_e32 v213, v68
	v_add_f32_e32 v66, v95, v66
	v_exp_f32_e32 v214, v69
	v_add_f32_e32 v66, v96, v66
	v_exp_f32_e32 v215, v70
	v_add_f32_e32 v66, v97, v66
	v_exp_f32_e32 v236, v71
	v_add_f32_e32 v66, v212, v66
	v_exp_f32_e32 v237, v72
	v_add_f32_e32 v66, v213, v66
	v_exp_f32_e32 v238, v73
	v_add_f32_e32 v66, v214, v66
	v_exp_f32_e32 v239, v74
	v_add_f32_e32 v66, v215, v66
	v_exp_f32_e32 v240, v75
	v_add_f32_e32 v66, v236, v66
	v_exp_f32_e32 v241, v76
	v_add_f32_e32 v66, v237, v66
	v_exp_f32_e32 v242, v77
	v_add_f32_e32 v66, v238, v66
	v_exp_f32_e32 v243, v78
	v_add_f32_e32 v66, v239, v66
	v_exp_f32_e32 v244, v79
	v_add_f32_e32 v66, v240, v66
	v_exp_f32_e32 v245, v80
	v_add_f32_e32 v66, v241, v66
	v_exp_f32_e32 v206, v206
	v_add_f32_e32 v66, v242, v66
	v_add_f32_e32 v66, v243, v66
	v_add_f32_e32 v66, v244, v66
	v_add_f32_e32 v66, v245, v66
	v_add_f32_e32 v234, v206, v66
	v_mov_b32_e32 v235, v234
	s_nop 1
	v_permlane32_swap_b32_e32 v234, v235
	v_cvt_pk_bf16_f32 v66, v81, v82
	v_cvt_pk_bf16_f32 v67, v83, v84
	v_cvt_pk_bf16_f32 v68, v85, v86
	v_cvt_pk_bf16_f32 v69, v87, v88
	v_cvt_pk_bf16_f32 v70, v89, v90
	v_cvt_pk_bf16_f32 v71, v91, v92
	v_cvt_pk_bf16_f32 v72, v93, v94
	v_cvt_pk_bf16_f32 v73, v95, v96
	v_cvt_pk_bf16_f32 v74, v97, v212
	v_cvt_pk_bf16_f32 v75, v213, v214
	v_cvt_pk_bf16_f32 v76, v215, v236
	v_cvt_pk_bf16_f32 v77, v237, v238
	v_cvt_pk_bf16_f32 v78, v239, v240
	v_cvt_pk_bf16_f32 v79, v241, v242
	v_cvt_pk_bf16_f32 v80, v243, v244
	v_cvt_pk_bf16_f32 v81, v245, v206
	s_nop 0
	v_permlane32_swap_b32_e32 v66, v68
	v_permlane32_swap_b32_e32 v67, v69
	v_permlane32_swap_b32_e32 v70, v72
	v_permlane32_swap_b32_e32 v71, v73
	v_permlane32_swap_b32_e32 v74, v76
	v_permlane32_swap_b32_e32 v75, v77
	v_permlane32_swap_b32_e32 v78, v80
	v_permlane32_swap_b32_e32 v79, v81
	ds_read_b64_tr_b16 v[82:83], v153 offset:0
	ds_read_b64_tr_b16 v[84:85], v153 offset:0x800
	ds_read_b64_tr_b16 v[86:87], v153 offset:0x1000
	ds_read_b64_tr_b16 v[88:89], v153 offset:0x1800
	ds_read_b64_tr_b16 v[90:91], v153 offset:0x2000
	ds_read_b64_tr_b16 v[92:93], v153 offset:0x2800
	ds_read_b64_tr_b16 v[94:95], v153 offset:0x3000
	ds_read_b64_tr_b16 v[96:97], v153 offset:0x3800
	s_nop 0
	s_waitcnt lgkmcnt(6)
	v_mfma_f32_32x32x16_bf16 v[50:65], v[66:69], v[82:85], v[50:65]
	ds_read_b64_tr_b16 v[82:83], v153 offset:0x200
	ds_read_b64_tr_b16 v[84:85], v153 offset:0xa00
	s_waitcnt lgkmcnt(6)
	v_mfma_f32_32x32x16_bf16 v[50:65], v[70:73], v[86:89], v[50:65]
	ds_read_b64_tr_b16 v[86:87], v153 offset:0x1200
	ds_read_b64_tr_b16 v[88:89], v153 offset:0x1a00
	s_waitcnt lgkmcnt(6)
	v_mfma_f32_32x32x16_bf16 v[50:65], v[74:77], v[90:93], v[50:65]
	ds_read_b64_tr_b16 v[90:91], v153 offset:0x2200
	ds_read_b64_tr_b16 v[92:93], v153 offset:0x2a00
	s_waitcnt lgkmcnt(6)
	v_mfma_f32_32x32x16_bf16 v[50:65], v[78:81], v[94:97], v[50:65]
	s_andn2_b64 vcc, exec, s[38:39]
	s_cbranch_vccnz .Lattn_sw0
	v_add_u32_e32 v250, s84, v157
	s_waitcnt vmcnt(3)
	ds_write_b128 v224, v[114:117] offset:32768
	s_waitcnt vmcnt(1)
	ds_write_b128 v224, v[122:125] offset:40960
	ds_write_b128 v250, v[118:121]
	v_add_u32_e32 v250, s84, v155
	s_waitcnt vmcnt(0)
	ds_write_b128 v250, v[126:129]
.Lattn_sw0:
	s_add_i32 s80, s99, 3
	s_cmp_lt_u32 s80, s79
	s_cselect_b64 s[72:73], -1, 0
	s_cmp_ge_u32 s80, s79
	s_cbranch_scc1 .Lattn_sl0
	v_add_co_u32_e32 v250, vcc, 0xffeb0000, v200
	s_nop 1
	v_addc_co_u32_e32 v251, vcc, -1, v201, vcc
	v_add_co_u32_e32 v252, vcc, 0xffee0000, v200
	s_nop 1
	v_addc_co_u32_e32 v253, vcc, -1, v201, vcc
	global_load_dwordx4 v[114:117], v[250:251], off offset:-2048
	global_load_dwordx4 v[118:121], v[250:251], off
	global_load_dwordx4 v[122:125], v[252:253], off offset:-2048
	global_load_dwordx4 v[126:129], v[252:253], off
.Lattn_sl0:
	ds_read_b64_tr_b16 v[94:95], v153 offset:0x3200
	ds_read_b64_tr_b16 v[96:97], v153 offset:0x3a00
	s_waitcnt lgkmcnt(6)
	v_mfma_f32_32x32x16_bf16 v[34:49], v[66:69], v[82:85], v[34:49]
	ds_read_b64_tr_b16 v[82:83], v153 offset:0x400
	ds_read_b64_tr_b16 v[84:85], v153 offset:0xc00
	s_waitcnt lgkmcnt(6)
	v_mfma_f32_32x32x16_bf16 v[34:49], v[70:73], v[86:89], v[34:49]
	ds_read_b64_tr_b16 v[86:87], v153 offset:0x1400
	ds_read_b64_tr_b16 v[88:89], v153 offset:0x1c00
	s_waitcnt lgkmcnt(6)
	v_mfma_f32_32x32x16_bf16 v[34:49], v[74:77], v[90:93], v[34:49]
	ds_read_b64_tr_b16 v[90:91], v153 offset:0x2400
	ds_read_b64_tr_b16 v[92:93], v153 offset:0x2c00
	s_waitcnt lgkmcnt(6)
	v_mfma_f32_32x32x16_bf16 v[34:49], v[78:81], v[94:97], v[34:49]
	ds_read_b64_tr_b16 v[94:95], v153 offset:0x3400
	ds_read_b64_tr_b16 v[96:97], v153 offset:0x3c00
	s_waitcnt lgkmcnt(6)
	v_mfma_f32_32x32x16_bf16 v[18:33], v[66:69], v[82:85], v[18:33]
	ds_read_b64_tr_b16 v[82:83], v153 offset:0x600
	ds_read_b64_tr_b16 v[84:85], v153 offset:0xe00
	s_waitcnt lgkmcnt(6)
	v_mfma_f32_32x32x16_bf16 v[18:33], v[70:73], v[86:89], v[18:33]
	ds_read_b64_tr_b16 v[86:87], v153 offset:0x1600
	ds_read_b64_tr_b16 v[88:89], v153 offset:0x1e00
	s_waitcnt lgkmcnt(6)
	v_mfma_f32_32x32x16_bf16 v[18:33], v[74:77], v[90:93], v[18:33]
	ds_read_b64_tr_b16 v[90:91], v153 offset:0x2600
	ds_read_b64_tr_b16 v[92:93], v153 offset:0x2e00
	s_waitcnt lgkmcnt(6)
	v_mfma_f32_32x32x16_bf16 v[18:33], v[78:81], v[94:97], v[18:33]
	ds_read_b64_tr_b16 v[94:95], v153 offset:0x3600
	ds_read_b64_tr_b16 v[96:97], v153 offset:0x3e00
	s_waitcnt lgkmcnt(6)
	v_mfma_f32_32x32x16_bf16 v[2:17], v[66:69], v[82:85], v[2:17]
	s_andn2_b64 vcc, exec, s[72:73]
	s_waitcnt lgkmcnt(4)
	v_mfma_f32_32x32x16_bf16 v[2:17], v[70:73], v[86:89], v[2:17]
	s_waitcnt lgkmcnt(2)
	v_mfma_f32_32x32x16_bf16 v[2:17], v[74:77], v[90:93], v[2:17]
	s_waitcnt lgkmcnt(0)
	v_mfma_f32_32x32x16_bf16 v[2:17], v[78:81], v[94:97], v[2:17]

.LBB0_185:
	v_cndmask_b32_e64 v233, v237, v233, s[8:9]
	v_mul_f32_e32 v206, 0xbe38aa3b, v233
	v_fmamk_f32 v82, v82, 0x3e38aa3b, v206
	v_fmamk_f32 v83, v83, 0x3e38aa3b, v206
	v_fmamk_f32 v84, v84, 0x3e38aa3b, v206
	v_fmamk_f32 v85, v85, 0x3e38aa3b, v206
	v_fmamk_f32 v86, v86, 0x3e38aa3b, v206
	v_fmamk_f32 v87, v87, 0x3e38aa3b, v206
	v_fmamk_f32 v88, v88, 0x3e38aa3b, v206
	v_fmamk_f32 v89, v89, 0x3e38aa3b, v206
	v_fmamk_f32 v90, v90, 0x3e38aa3b, v206
	v_fmamk_f32 v91, v91, 0x3e38aa3b, v206
	v_fmamk_f32 v92, v92, 0x3e38aa3b, v206
	v_fmamk_f32 v93, v93, 0x3e38aa3b, v206
	v_fmamk_f32 v94, v94, 0x3e38aa3b, v206
	v_fmamk_f32 v95, v95, 0x3e38aa3b, v206
	v_fmamk_f32 v96, v96, 0x3e38aa3b, v206
	v_fmamk_f32 v97, v97, 0x3e38aa3b, v206
	v_fmamk_f32 v66, v66, 0x3e38aa3b, v206
	v_fmamk_f32 v67, v67, 0x3e38aa3b, v206
	v_fmamk_f32 v68, v68, 0x3e38aa3b, v206
	v_fmamk_f32 v69, v69, 0x3e38aa3b, v206
	v_fmamk_f32 v70, v70, 0x3e38aa3b, v206
	v_fmamk_f32 v71, v71, 0x3e38aa3b, v206
	v_fmamk_f32 v72, v72, 0x3e38aa3b, v206
	v_fmamk_f32 v73, v73, 0x3e38aa3b, v206
	v_fmamk_f32 v74, v74, 0x3e38aa3b, v206
	v_fmamk_f32 v75, v75, 0x3e38aa3b, v206
	v_fmamk_f32 v76, v76, 0x3e38aa3b, v206
	v_fmamk_f32 v77, v77, 0x3e38aa3b, v206
	v_fmamk_f32 v78, v78, 0x3e38aa3b, v206
	v_fmamk_f32 v79, v79, 0x3e38aa3b, v206
	v_fmamk_f32 v80, v80, 0x3e38aa3b, v206
	v_fmac_f32_e32 v206, 0x3e38aa3b, v81
	v_exp_f32_e32 v81, v82
	v_exp_f32_e32 v82, v83
	v_exp_f32_e32 v83, v84
	v_exp_f32_e32 v84, v85
	v_exp_f32_e32 v85, v86
	v_exp_f32_e32 v86, v87
	v_exp_f32_e32 v87, v88
	v_exp_f32_e32 v88, v89
	v_exp_f32_e32 v89, v90
	v_exp_f32_e32 v90, v91
	v_exp_f32_e32 v91, v92
	v_exp_f32_e32 v92, v93
	v_exp_f32_e32 v93, v94
	v_exp_f32_e32 v94, v95
	v_exp_f32_e32 v95, v96
	v_exp_f32_e32 v96, v97
	v_add_f32_e32 v97, v234, v235
	v_fmac_f32_e32 v97, v232, v1
	v_exp_f32_e32 v1, v66
	v_add_f32_e32 v66, 0, v81
	v_add_f32_e32 v66, v82, v66
	v_add_f32_e32 v66, v83, v66
	v_add_f32_e32 v66, v84, v66
	v_add_f32_e32 v66, v85, v66
	v_add_f32_e32 v66, v86, v66
	v_add_f32_e32 v66, v87, v66
	v_add_f32_e32 v66, v88, v66
	v_add_f32_e32 v66, v89, v66
	v_add_f32_e32 v66, v90, v66
	v_add_f32_e32 v66, v91, v66
	v_add_f32_e32 v66, v92, v66
	v_add_f32_e32 v66, v93, v66
	v_exp_f32_e32 v212, v67
	v_add_f32_e32 v66, v94, v66
	v_exp_f32_e32 v213, v68
	v_add_f32_e32 v66, v95, v66
	v_exp_f32_e32 v214, v69
	v_add_f32_e32 v66, v96, v66
	v_exp_f32_e32 v215, v70
	v_add_f32_e32 v66, v1, v66
	v_exp_f32_e32 v234, v71
	v_add_f32_e32 v66, v212, v66
	v_exp_f32_e32 v235, v72
	v_add_f32_e32 v66, v213, v66
	v_exp_f32_e32 v237, v73
	v_add_f32_e32 v66, v214, v66
	v_exp_f32_e32 v238, v74
	v_add_f32_e32 v66, v215, v66
	v_exp_f32_e32 v239, v75
	v_add_f32_e32 v66, v234, v66
	v_exp_f32_e32 v240, v76
	v_add_f32_e32 v66, v235, v66
	v_exp_f32_e32 v241, v77
	v_add_f32_e32 v66, v237, v66
	v_exp_f32_e32 v242, v78
	v_add_f32_e32 v66, v238, v66
	v_exp_f32_e32 v243, v79
	v_add_f32_e32 v66, v239, v66
	v_exp_f32_e32 v244, v80
	v_add_f32_e32 v66, v240, v66
	v_exp_f32_e32 v206, v206
	v_add_f32_e32 v66, v241, v66
	v_add_f32_e32 v66, v242, v66
	v_add_f32_e32 v66, v243, v66
	v_add_f32_e32 v66, v244, v66
	v_add_f32_e32 v66, v206, v66
	v_mov_b32_e32 v67, v66
	s_nop 1
	v_permlane32_swap_b32_e32 v66, v67
	v_add_f32_e32 v232, v66, v67
	v_fmac_f32_e32 v232, v97, v236
	v_cvt_pk_bf16_f32 v66, v81, v82
	v_cvt_pk_bf16_f32 v67, v83, v84
	v_cvt_pk_bf16_f32 v68, v85, v86
	v_cvt_pk_bf16_f32 v69, v87, v88
	v_cvt_pk_bf16_f32 v70, v89, v90
	v_cvt_pk_bf16_f32 v71, v91, v92
	v_cvt_pk_bf16_f32 v72, v93, v94
	v_cvt_pk_bf16_f32 v73, v95, v96
	v_cvt_pk_bf16_f32 v74, v1, v212
	v_cvt_pk_bf16_f32 v75, v213, v214
	v_cvt_pk_bf16_f32 v76, v215, v234
	v_cvt_pk_bf16_f32 v77, v235, v237
	v_cvt_pk_bf16_f32 v78, v238, v239
	v_cvt_pk_bf16_f32 v79, v240, v241
	v_cvt_pk_bf16_f32 v80, v242, v243
	v_cvt_pk_bf16_f32 v81, v244, v206
	s_nop 0
	v_permlane32_swap_b32_e32 v66, v68
	v_permlane32_swap_b32_e32 v67, v69
	v_permlane32_swap_b32_e32 v70, v72
	v_permlane32_swap_b32_e32 v71, v73
	v_permlane32_swap_b32_e32 v74, v76
	v_permlane32_swap_b32_e32 v75, v77
	v_permlane32_swap_b32_e32 v78, v80
	v_permlane32_swap_b32_e32 v79, v81
	ds_read_b64_tr_b16 v[82:83], v153 offset:0x4000
	ds_read_b64_tr_b16 v[84:85], v153 offset:0x4800
	ds_read_b64_tr_b16 v[86:87], v153 offset:0x5000
	ds_read_b64_tr_b16 v[88:89], v153 offset:0x5800
	ds_read_b64_tr_b16 v[90:91], v153 offset:0x6000
	ds_read_b64_tr_b16 v[92:93], v153 offset:0x6800
	ds_read_b64_tr_b16 v[94:95], v153 offset:0x7000
	ds_read_b64_tr_b16 v[96:97], v153 offset:0x7800
	s_nop 0
	s_waitcnt lgkmcnt(6)
	v_mfma_f32_32x32x16_bf16 v[50:65], v[66:69], v[82:85], v[50:65]
	ds_read_b64_tr_b16 v[82:83], v153 offset:0x4200
	ds_read_b64_tr_b16 v[84:85], v153 offset:0x4a00
	s_waitcnt lgkmcnt(6)
	v_mfma_f32_32x32x16_bf16 v[50:65], v[70:73], v[86:89], v[50:65]
	ds_read_b64_tr_b16 v[86:87], v153 offset:0x5200
	ds_read_b64_tr_b16 v[88:89], v153 offset:0x5a00
	s_waitcnt lgkmcnt(6)
	v_mfma_f32_32x32x16_bf16 v[50:65], v[74:77], v[90:93], v[50:65]
	ds_read_b64_tr_b16 v[90:91], v153 offset:0x6200
	ds_read_b64_tr_b16 v[92:93], v153 offset:0x6a00
	s_waitcnt lgkmcnt(6)
	v_mfma_f32_32x32x16_bf16 v[50:65], v[78:81], v[94:97], v[50:65]
	s_andn2_b64 vcc, exec, s[72:73]
	s_cbranch_vccnz .Lattn_sw1
	v_add_u32_e32 v250, s88, v157
	s_waitcnt vmcnt(3)
	ds_write_b128 v224, v[114:117] offset:49152
	s_waitcnt vmcnt(1)
	ds_write_b128 v224, v[122:125] offset:57344
	ds_write_b128 v250, v[118:121]
	v_add_u32_e32 v250, s88, v155
	s_waitcnt vmcnt(0)
	ds_write_b128 v250, v[126:129]
.Lattn_sw1:
	s_add_i32 s80, s80, 1
	s_cmp_le_u32 s80, s33
	s_cselect_b64 s[72:73], -1, 0
	s_cmp_gt_u32 s80, s33
	s_cbranch_scc1 .Lattn_sl1
	v_add_co_u32_e32 v250, vcc, 0xfff10000, v200
	s_nop 1
	v_addc_co_u32_e32 v251, vcc, -1, v201, vcc
	v_add_co_u32_e32 v252, vcc, 0xfff40000, v200
	s_nop 1
	v_addc_co_u32_e32 v253, vcc, -1, v201, vcc
	global_load_dwordx4 v[114:117], v[250:251], off offset:-2048
	global_load_dwordx4 v[118:121], v[250:251], off
	global_load_dwordx4 v[122:125], v[252:253], off offset:-2048
	global_load_dwordx4 v[126:129], v[252:253], off
.Lattn_sl1:
	ds_read_b64_tr_b16 v[94:95], v153 offset:0x7200
	ds_read_b64_tr_b16 v[96:97], v153 offset:0x7a00
	s_waitcnt lgkmcnt(6)
	v_mfma_f32_32x32x16_bf16 v[34:49], v[66:69], v[82:85], v[34:49]
	ds_read_b64_tr_b16 v[82:83], v153 offset:0x4400
	ds_read_b64_tr_b16 v[84:85], v153 offset:0x4c00
	s_waitcnt lgkmcnt(6)
	v_mfma_f32_32x32x16_bf16 v[34:49], v[70:73], v[86:89], v[34:49]
	ds_read_b64_tr_b16 v[86:87], v153 offset:0x5400
	ds_read_b64_tr_b16 v[88:89], v153 offset:0x5c00
	s_waitcnt lgkmcnt(6)
	v_mfma_f32_32x32x16_bf16 v[34:49], v[74:77], v[90:93], v[34:49]
	ds_read_b64_tr_b16 v[90:91], v153 offset:0x6400
	ds_read_b64_tr_b16 v[92:93], v153 offset:0x6c00
	s_waitcnt lgkmcnt(6)
	v_mfma_f32_32x32x16_bf16 v[34:49], v[78:81], v[94:97], v[34:49]
	ds_read_b64_tr_b16 v[94:95], v153 offset:0x7400
	ds_read_b64_tr_b16 v[96:97], v153 offset:0x7c00
	s_waitcnt lgkmcnt(6)
	v_mfma_f32_32x32x16_bf16 v[18:33], v[66:69], v[82:85], v[18:33]
	ds_read_b64_tr_b16 v[82:83], v153 offset:0x4600
	ds_read_b64_tr_b16 v[84:85], v153 offset:0x4e00
	s_waitcnt lgkmcnt(6)
	v_mfma_f32_32x32x16_bf16 v[18:33], v[70:73], v[86:89], v[18:33]
	ds_read_b64_tr_b16 v[86:87], v153 offset:0x5600
	ds_read_b64_tr_b16 v[88:89], v153 offset:0x5e00
	s_waitcnt lgkmcnt(6)
	v_mfma_f32_32x32x16_bf16 v[18:33], v[74:77], v[90:93], v[18:33]
	ds_read_b64_tr_b16 v[90:91], v153 offset:0x6600
	ds_read_b64_tr_b16 v[92:93], v153 offset:0x6e00
	s_waitcnt lgkmcnt(6)
	v_mfma_f32_32x32x16_bf16 v[18:33], v[78:81], v[94:97], v[18:33]
	ds_read_b64_tr_b16 v[94:95], v153 offset:0x7600
	ds_read_b64_tr_b16 v[96:97], v153 offset:0x7e00
	s_waitcnt lgkmcnt(6)
	v_mfma_f32_32x32x16_bf16 v[2:17], v[66:69], v[82:85], v[2:17]
	s_andn2_b64 vcc, exec, s[38:39]
	s_waitcnt lgkmcnt(0)
	s_barrier
	s_waitcnt lgkmcnt(4)
	v_mfma_f32_32x32x16_bf16 v[2:17], v[70:73], v[86:89], v[2:17]
	s_waitcnt lgkmcnt(2)
	v_mfma_f32_32x32x16_bf16 v[2:17], v[74:77], v[90:93], v[2:17]
	s_waitcnt lgkmcnt(0)
	v_mfma_f32_32x32x16_bf16 v[2:17], v[78:81], v[94:97], v[2:17]
	s_cbranch_vccnz .LBB0_207

.LBB0_196:
	v_cndmask_b32_e64 v233, v234, v233, s[8:9]
	v_mul_f32_e32 v206, 0xbe38aa3b, v233
	v_fmamk_f32 v82, v82, 0x3e38aa3b, v206
	v_fmamk_f32 v83, v83, 0x3e38aa3b, v206
	v_fmamk_f32 v84, v84, 0x3e38aa3b, v206
	v_fmamk_f32 v85, v85, 0x3e38aa3b, v206
	v_fmamk_f32 v86, v86, 0x3e38aa3b, v206
	v_fmamk_f32 v87, v87, 0x3e38aa3b, v206
	v_fmamk_f32 v88, v88, 0x3e38aa3b, v206
	v_fmamk_f32 v89, v89, 0x3e38aa3b, v206
	v_fmamk_f32 v90, v90, 0x3e38aa3b, v206
	v_fmamk_f32 v91, v91, 0x3e38aa3b, v206
	v_fmamk_f32 v92, v92, 0x3e38aa3b, v206
	v_fmamk_f32 v93, v93, 0x3e38aa3b, v206
	v_fmamk_f32 v94, v94, 0x3e38aa3b, v206
	v_fmamk_f32 v95, v95, 0x3e38aa3b, v206
	v_fmamk_f32 v96, v96, 0x3e38aa3b, v206
	v_fmamk_f32 v97, v97, 0x3e38aa3b, v206
	v_fmamk_f32 v66, v66, 0x3e38aa3b, v206
	v_fmamk_f32 v67, v67, 0x3e38aa3b, v206
	v_fmamk_f32 v68, v68, 0x3e38aa3b, v206
	v_fmamk_f32 v69, v69, 0x3e38aa3b, v206
	v_fmamk_f32 v70, v70, 0x3e38aa3b, v206
	v_fmamk_f32 v71, v71, 0x3e38aa3b, v206
	v_fmamk_f32 v72, v72, 0x3e38aa3b, v206
	v_fmamk_f32 v73, v73, 0x3e38aa3b, v206
	v_fmamk_f32 v74, v74, 0x3e38aa3b, v206
	v_fmamk_f32 v75, v75, 0x3e38aa3b, v206
	v_fmamk_f32 v76, v76, 0x3e38aa3b, v206
	v_fmamk_f32 v77, v77, 0x3e38aa3b, v206
	v_fmamk_f32 v78, v78, 0x3e38aa3b, v206
	v_fmamk_f32 v79, v79, 0x3e38aa3b, v206
	v_fmamk_f32 v80, v80, 0x3e38aa3b, v206
	v_fmac_f32_e32 v206, 0x3e38aa3b, v81
	v_exp_f32_e32 v81, v82
	v_exp_f32_e32 v82, v83
	v_exp_f32_e32 v83, v84
	v_exp_f32_e32 v84, v85
	v_exp_f32_e32 v85, v86
	v_exp_f32_e32 v86, v87
	v_exp_f32_e32 v87, v88
	v_exp_f32_e32 v88, v89
	v_exp_f32_e32 v89, v90
	v_exp_f32_e32 v90, v91
	v_exp_f32_e32 v91, v92
	v_exp_f32_e32 v92, v93
	v_exp_f32_e32 v93, v94
	v_exp_f32_e32 v94, v95
	v_exp_f32_e32 v95, v96
	v_exp_f32_e32 v96, v97
	v_exp_f32_e32 v97, v66
	v_add_f32_e32 v66, 0, v81
	v_add_f32_e32 v66, v82, v66
	v_add_f32_e32 v66, v83, v66
	v_add_f32_e32 v66, v84, v66
	v_add_f32_e32 v66, v85, v66
	v_add_f32_e32 v66, v86, v66
	v_add_f32_e32 v66, v87, v66
	v_add_f32_e32 v66, v88, v66
	v_add_f32_e32 v66, v89, v66
	v_add_f32_e32 v66, v90, v66
	v_add_f32_e32 v66, v91, v66
	v_add_f32_e32 v66, v92, v66
	v_add_f32_e32 v66, v93, v66
	v_exp_f32_e32 v212, v67
	v_add_f32_e32 v66, v94, v66
	v_exp_f32_e32 v213, v68
	v_add_f32_e32 v66, v95, v66
	v_exp_f32_e32 v214, v69
	v_add_f32_e32 v66, v96, v66
	v_exp_f32_e32 v215, v70
	v_add_f32_e32 v66, v97, v66
	v_exp_f32_e32 v236, v71
	v_add_f32_e32 v66, v212, v66
	v_exp_f32_e32 v237, v72
	v_add_f32_e32 v66, v213, v66
	v_exp_f32_e32 v238, v73
	v_add_f32_e32 v66, v214, v66
	v_exp_f32_e32 v239, v74
	v_add_f32_e32 v66, v215, v66
	v_exp_f32_e32 v240, v75
	v_add_f32_e32 v66, v236, v66
	v_exp_f32_e32 v241, v76
	v_add_f32_e32 v66, v237, v66
	v_exp_f32_e32 v242, v77
	v_add_f32_e32 v66, v238, v66
	v_exp_f32_e32 v243, v78
	v_add_f32_e32 v66, v239, v66
	v_exp_f32_e32 v244, v79
	v_add_f32_e32 v66, v240, v66
	v_exp_f32_e32 v245, v80
	v_add_f32_e32 v66, v241, v66
	v_exp_f32_e32 v206, v206
	v_add_f32_e32 v66, v242, v66
	v_add_f32_e32 v66, v243, v66
	v_add_f32_e32 v66, v244, v66
	v_add_f32_e32 v66, v245, v66
	v_add_f32_e32 v234, v206, v66
	v_mov_b32_e32 v235, v234
	s_nop 1
	v_permlane32_swap_b32_e32 v234, v235
	v_cvt_pk_bf16_f32 v66, v81, v82
	v_cvt_pk_bf16_f32 v67, v83, v84
	v_cvt_pk_bf16_f32 v68, v85, v86
	v_cvt_pk_bf16_f32 v69, v87, v88
	v_cvt_pk_bf16_f32 v70, v89, v90
	v_cvt_pk_bf16_f32 v71, v91, v92
	v_cvt_pk_bf16_f32 v72, v93, v94
	v_cvt_pk_bf16_f32 v73, v95, v96
	v_cvt_pk_bf16_f32 v74, v97, v212
	v_cvt_pk_bf16_f32 v75, v213, v214
	v_cvt_pk_bf16_f32 v76, v215, v236
	v_cvt_pk_bf16_f32 v77, v237, v238
	v_cvt_pk_bf16_f32 v78, v239, v240
	v_cvt_pk_bf16_f32 v79, v241, v242
	v_cvt_pk_bf16_f32 v80, v243, v244
	v_cvt_pk_bf16_f32 v81, v245, v206
	s_nop 0
	v_permlane32_swap_b32_e32 v66, v68
	v_permlane32_swap_b32_e32 v67, v69
	v_permlane32_swap_b32_e32 v70, v72
	v_permlane32_swap_b32_e32 v71, v73
	v_permlane32_swap_b32_e32 v74, v76
	v_permlane32_swap_b32_e32 v75, v77
	v_permlane32_swap_b32_e32 v78, v80
	v_permlane32_swap_b32_e32 v79, v81
	ds_read_b64_tr_b16 v[82:83], v153 offset:0x8000
	ds_read_b64_tr_b16 v[84:85], v153 offset:0x8800
	ds_read_b64_tr_b16 v[86:87], v153 offset:0x9000
	ds_read_b64_tr_b16 v[88:89], v153 offset:0x9800
	ds_read_b64_tr_b16 v[90:91], v153 offset:0xa000
	ds_read_b64_tr_b16 v[92:93], v153 offset:0xa800
	ds_read_b64_tr_b16 v[94:95], v153 offset:0xb000
	ds_read_b64_tr_b16 v[96:97], v153 offset:0xb800
	s_nop 0
	s_waitcnt lgkmcnt(6)
	v_mfma_f32_32x32x16_bf16 v[50:65], v[66:69], v[82:85], v[50:65]
	ds_read_b64_tr_b16 v[82:83], v153 offset:0x8200
	ds_read_b64_tr_b16 v[84:85], v153 offset:0x8a00
	s_waitcnt lgkmcnt(6)
	v_mfma_f32_32x32x16_bf16 v[50:65], v[70:73], v[86:89], v[50:65]
	ds_read_b64_tr_b16 v[86:87], v153 offset:0x9200
	ds_read_b64_tr_b16 v[88:89], v153 offset:0x9a00
	s_waitcnt lgkmcnt(6)
	v_mfma_f32_32x32x16_bf16 v[50:65], v[74:77], v[90:93], v[50:65]
	ds_read_b64_tr_b16 v[90:91], v153 offset:0xa200
	ds_read_b64_tr_b16 v[92:93], v153 offset:0xaa00
	s_waitcnt lgkmcnt(6)
	v_mfma_f32_32x32x16_bf16 v[50:65], v[78:81], v[94:97], v[50:65]
	s_andn2_b64 vcc, exec, s[72:73]
	s_cbranch_vccnz .Lattn_sw2
	s_waitcnt vmcnt(3)
	ds_write_b128 v224, v[114:117]
	s_waitcnt vmcnt(1)
	ds_write_b128 v224, v[122:125] offset:8192
	ds_write_b128 v173, v[118:121]
	s_waitcnt vmcnt(0)
	ds_write_b128 v175, v[126:129]
.Lattn_sw2:
	s_add_i32 s8, s99, 5
	s_cmp_lt_u32 s8, s79
	s_cselect_b64 s[38:39], -1, 0
	s_cmp_ge_u32 s8, s79
	s_cbranch_scc1 .Lattn_sl2
	v_add_co_u32_e32 v250, vcc, 0xfff70000, v200
	s_nop 1
	v_addc_co_u32_e32 v251, vcc, -1, v201, vcc
	v_add_co_u32_e32 v252, vcc, 0xfffa0000, v200
	s_nop 1
	v_addc_co_u32_e32 v253, vcc, -1, v201, vcc
	global_load_dwordx4 v[114:117], v[250:251], off offset:-2048
	global_load_dwordx4 v[118:121], v[250:251], off
	global_load_dwordx4 v[122:125], v[252:253], off offset:-2048
	global_load_dwordx4 v[126:129], v[252:253], off
.Lattn_sl2:
	ds_read_b64_tr_b16 v[94:95], v153 offset:0xb200
	ds_read_b64_tr_b16 v[96:97], v153 offset:0xba00
	s_waitcnt lgkmcnt(6)
	v_mfma_f32_32x32x16_bf16 v[34:49], v[66:69], v[82:85], v[34:49]
	ds_read_b64_tr_b16 v[82:83], v153 offset:0x8400
	ds_read_b64_tr_b16 v[84:85], v153 offset:0x8c00
	s_waitcnt lgkmcnt(6)
	v_mfma_f32_32x32x16_bf16 v[34:49], v[70:73], v[86:89], v[34:49]
	ds_read_b64_tr_b16 v[86:87], v153 offset:0x9400
	ds_read_b64_tr_b16 v[88:89], v153 offset:0x9c00
	s_waitcnt lgkmcnt(6)
	v_mfma_f32_32x32x16_bf16 v[34:49], v[74:77], v[90:93], v[34:49]
	ds_read_b64_tr_b16 v[90:91], v153 offset:0xa400
	ds_read_b64_tr_b16 v[92:93], v153 offset:0xac00
	s_waitcnt lgkmcnt(6)
	v_mfma_f32_32x32x16_bf16 v[34:49], v[78:81], v[94:97], v[34:49]
	ds_read_b64_tr_b16 v[94:95], v153 offset:0xb400
	ds_read_b64_tr_b16 v[96:97], v153 offset:0xbc00
	s_waitcnt lgkmcnt(6)
	v_mfma_f32_32x32x16_bf16 v[18:33], v[66:69], v[82:85], v[18:33]
	ds_read_b64_tr_b16 v[82:83], v153 offset:0x8600
	ds_read_b64_tr_b16 v[84:85], v153 offset:0x8e00
	s_waitcnt lgkmcnt(6)
	v_mfma_f32_32x32x16_bf16 v[18:33], v[70:73], v[86:89], v[18:33]
	ds_read_b64_tr_b16 v[86:87], v153 offset:0x9600
	ds_read_b64_tr_b16 v[88:89], v153 offset:0x9e00
	s_waitcnt lgkmcnt(6)
	v_mfma_f32_32x32x16_bf16 v[18:33], v[74:77], v[90:93], v[18:33]
	ds_read_b64_tr_b16 v[90:91], v153 offset:0xa600
	ds_read_b64_tr_b16 v[92:93], v153 offset:0xae00
	s_waitcnt lgkmcnt(6)
	v_mfma_f32_32x32x16_bf16 v[18:33], v[78:81], v[94:97], v[18:33]
	ds_read_b64_tr_b16 v[94:95], v153 offset:0xb600
	ds_read_b64_tr_b16 v[96:97], v153 offset:0xbe00
	s_waitcnt lgkmcnt(6)
	v_mfma_f32_32x32x16_bf16 v[2:17], v[66:69], v[82:85], v[2:17]
	s_andn2_b64 vcc, exec, s[38:39]
	s_waitcnt lgkmcnt(4)
	v_mfma_f32_32x32x16_bf16 v[2:17], v[70:73], v[86:89], v[2:17]
	s_waitcnt lgkmcnt(2)
	v_mfma_f32_32x32x16_bf16 v[2:17], v[74:77], v[90:93], v[2:17]
	s_waitcnt lgkmcnt(0)
	v_mfma_f32_32x32x16_bf16 v[2:17], v[78:81], v[94:97], v[2:17]

.LBB0_206:
	v_cndmask_b32_e64 v233, v237, v233, s[8:9]
	v_mul_f32_e32 v206, 0xbe38aa3b, v233
	v_fmamk_f32 v82, v82, 0x3e38aa3b, v206
	v_fmamk_f32 v83, v83, 0x3e38aa3b, v206
	v_fmamk_f32 v84, v84, 0x3e38aa3b, v206
	v_fmamk_f32 v85, v85, 0x3e38aa3b, v206
	v_fmamk_f32 v86, v86, 0x3e38aa3b, v206
	v_fmamk_f32 v87, v87, 0x3e38aa3b, v206
	v_fmamk_f32 v88, v88, 0x3e38aa3b, v206
	v_fmamk_f32 v89, v89, 0x3e38aa3b, v206
	v_fmamk_f32 v90, v90, 0x3e38aa3b, v206
	v_fmamk_f32 v91, v91, 0x3e38aa3b, v206
	v_fmamk_f32 v92, v92, 0x3e38aa3b, v206
	v_fmamk_f32 v93, v93, 0x3e38aa3b, v206
	v_fmamk_f32 v94, v94, 0x3e38aa3b, v206
	v_fmamk_f32 v95, v95, 0x3e38aa3b, v206
	v_fmamk_f32 v96, v96, 0x3e38aa3b, v206
	v_fmamk_f32 v97, v97, 0x3e38aa3b, v206
	v_fmamk_f32 v66, v66, 0x3e38aa3b, v206
	v_fmamk_f32 v67, v67, 0x3e38aa3b, v206
	v_fmamk_f32 v68, v68, 0x3e38aa3b, v206
	v_fmamk_f32 v69, v69, 0x3e38aa3b, v206
	v_fmamk_f32 v70, v70, 0x3e38aa3b, v206
	v_fmamk_f32 v71, v71, 0x3e38aa3b, v206
	v_fmamk_f32 v72, v72, 0x3e38aa3b, v206
	v_fmamk_f32 v73, v73, 0x3e38aa3b, v206
	v_fmamk_f32 v74, v74, 0x3e38aa3b, v206
	v_fmamk_f32 v75, v75, 0x3e38aa3b, v206
	v_fmamk_f32 v76, v76, 0x3e38aa3b, v206
	v_fmamk_f32 v77, v77, 0x3e38aa3b, v206
	v_fmamk_f32 v78, v78, 0x3e38aa3b, v206
	v_fmamk_f32 v79, v79, 0x3e38aa3b, v206
	v_fmamk_f32 v80, v80, 0x3e38aa3b, v206
	v_fmac_f32_e32 v206, 0x3e38aa3b, v81
	v_exp_f32_e32 v81, v82
	v_exp_f32_e32 v82, v83
	v_exp_f32_e32 v83, v84
	v_exp_f32_e32 v84, v85
	v_exp_f32_e32 v85, v86
	v_exp_f32_e32 v86, v87
	v_exp_f32_e32 v87, v88
	v_exp_f32_e32 v88, v89
	v_exp_f32_e32 v89, v90
	v_exp_f32_e32 v90, v91
	v_exp_f32_e32 v91, v92
	v_exp_f32_e32 v92, v93
	v_exp_f32_e32 v93, v94
	v_exp_f32_e32 v94, v95
	v_exp_f32_e32 v95, v96
	v_exp_f32_e32 v96, v97
	v_add_f32_e32 v97, v234, v235
	v_fmac_f32_e32 v97, v232, v1
	v_exp_f32_e32 v1, v66
	v_add_f32_e32 v66, 0, v81
	v_add_f32_e32 v66, v82, v66
	v_add_f32_e32 v66, v83, v66
	v_add_f32_e32 v66, v84, v66
	v_add_f32_e32 v66, v85, v66
	v_add_f32_e32 v66, v86, v66
	v_add_f32_e32 v66, v87, v66
	v_add_f32_e32 v66, v88, v66
	v_add_f32_e32 v66, v89, v66
	v_add_f32_e32 v66, v90, v66
	v_add_f32_e32 v66, v91, v66
	v_add_f32_e32 v66, v92, v66
	v_add_f32_e32 v66, v93, v66
	v_exp_f32_e32 v212, v67
	v_add_f32_e32 v66, v94, v66
	v_exp_f32_e32 v213, v68
	v_add_f32_e32 v66, v95, v66
	v_exp_f32_e32 v214, v69
	v_add_f32_e32 v66, v96, v66
	v_exp_f32_e32 v215, v70
	v_add_f32_e32 v66, v1, v66
	v_exp_f32_e32 v234, v71
	v_add_f32_e32 v66, v212, v66
	v_exp_f32_e32 v235, v72
	v_add_f32_e32 v66, v213, v66
	v_exp_f32_e32 v237, v73
	v_add_f32_e32 v66, v214, v66
	v_exp_f32_e32 v238, v74
	v_add_f32_e32 v66, v215, v66
	v_exp_f32_e32 v239, v75
	v_add_f32_e32 v66, v234, v66
	v_exp_f32_e32 v240, v76
	v_add_f32_e32 v66, v235, v66
	v_exp_f32_e32 v241, v77
	v_add_f32_e32 v66, v237, v66
	v_exp_f32_e32 v242, v78
	v_add_f32_e32 v66, v238, v66
	v_exp_f32_e32 v243, v79
	v_add_f32_e32 v66, v239, v66
	v_exp_f32_e32 v244, v80
	v_add_f32_e32 v66, v240, v66
	v_exp_f32_e32 v206, v206
	v_add_f32_e32 v66, v241, v66
	v_add_f32_e32 v66, v242, v66
	v_add_f32_e32 v66, v243, v66
	v_add_f32_e32 v66, v244, v66
	v_add_f32_e32 v66, v206, v66
	v_mov_b32_e32 v67, v66
	s_nop 1
	v_permlane32_swap_b32_e32 v66, v67
	v_add_f32_e32 v232, v66, v67
	v_fmac_f32_e32 v232, v97, v236
	v_cvt_pk_bf16_f32 v66, v81, v82
	v_cvt_pk_bf16_f32 v67, v83, v84
	v_cvt_pk_bf16_f32 v68, v85, v86
	v_cvt_pk_bf16_f32 v69, v87, v88
	v_cvt_pk_bf16_f32 v70, v89, v90
	v_cvt_pk_bf16_f32 v71, v91, v92
	v_cvt_pk_bf16_f32 v72, v93, v94
	v_cvt_pk_bf16_f32 v73, v95, v96
	v_cvt_pk_bf16_f32 v74, v1, v212
	v_cvt_pk_bf16_f32 v75, v213, v214
	v_cvt_pk_bf16_f32 v76, v215, v234
	v_cvt_pk_bf16_f32 v77, v235, v237
	v_cvt_pk_bf16_f32 v78, v238, v239
	v_cvt_pk_bf16_f32 v79, v240, v241
	v_cvt_pk_bf16_f32 v80, v242, v243
	v_cvt_pk_bf16_f32 v81, v244, v206
	s_nop 0
	v_permlane32_swap_b32_e32 v66, v68
	v_permlane32_swap_b32_e32 v67, v69
	v_permlane32_swap_b32_e32 v70, v72
	v_permlane32_swap_b32_e32 v71, v73
	v_permlane32_swap_b32_e32 v74, v76
	v_permlane32_swap_b32_e32 v75, v77
	v_permlane32_swap_b32_e32 v78, v80
	v_permlane32_swap_b32_e32 v79, v81
	ds_read_b64_tr_b16 v[82:83], v153 offset:0xc000
	ds_read_b64_tr_b16 v[84:85], v153 offset:0xc800
	ds_read_b64_tr_b16 v[86:87], v153 offset:0xd000
	ds_read_b64_tr_b16 v[88:89], v153 offset:0xd800
	ds_read_b64_tr_b16 v[90:91], v153 offset:0xe000
	ds_read_b64_tr_b16 v[92:93], v153 offset:0xe800
	ds_read_b64_tr_b16 v[94:95], v153 offset:0xf000
	ds_read_b64_tr_b16 v[96:97], v153 offset:0xf800
	s_nop 0
	s_waitcnt lgkmcnt(6)
	v_mfma_f32_32x32x16_bf16 v[50:65], v[66:69], v[82:85], v[50:65]
	ds_read_b64_tr_b16 v[82:83], v153 offset:0xc200
	ds_read_b64_tr_b16 v[84:85], v153 offset:0xca00
	s_waitcnt lgkmcnt(6)
	v_mfma_f32_32x32x16_bf16 v[50:65], v[70:73], v[86:89], v[50:65]
	ds_read_b64_tr_b16 v[86:87], v153 offset:0xd200
	ds_read_b64_tr_b16 v[88:89], v153 offset:0xda00
	s_waitcnt lgkmcnt(6)
	v_mfma_f32_32x32x16_bf16 v[50:65], v[74:77], v[90:93], v[50:65]
	ds_read_b64_tr_b16 v[90:91], v153 offset:0xe200
	ds_read_b64_tr_b16 v[92:93], v153 offset:0xea00
	s_waitcnt lgkmcnt(6)
	v_mfma_f32_32x32x16_bf16 v[50:65], v[78:81], v[94:97], v[50:65]
	s_andn2_b64 vcc, exec, s[38:39]
	s_cbranch_vccnz .Lattn_sw3
	s_waitcnt vmcnt(3)
	ds_write_b128 v224, v[114:117] offset:16384
	s_waitcnt vmcnt(1)
	ds_write_b128 v224, v[122:125] offset:24576
	ds_write_b128 v229, v[118:121]
	s_waitcnt vmcnt(0)
	ds_write_b128 v230, v[126:129]
.Lattn_sw3:
	s_add_i32 s8, s99, 6
	s_cmp_gt_u32 s8, s33
	s_cbranch_scc1 .Lattn_sl3
	v_add_co_u32_e32 v250, vcc, 0xfffd0000, v200
	s_nop 1
	v_addc_co_u32_e32 v251, vcc, -1, v201, vcc
	global_load_dwordx4 v[114:117], v[250:251], off offset:-2048
	global_load_dwordx4 v[118:121], v[250:251], off
	global_load_dwordx4 v[122:125], v[200:201], off offset:-2048
	global_load_dwordx4 v[126:129], v[200:201], off
.Lattn_sl3:
	ds_read_b64_tr_b16 v[94:95], v153 offset:0xf200
	ds_read_b64_tr_b16 v[96:97], v153 offset:0xfa00
	s_waitcnt lgkmcnt(6)
	v_mfma_f32_32x32x16_bf16 v[34:49], v[66:69], v[82:85], v[34:49]
	ds_read_b64_tr_b16 v[82:83], v153 offset:0xc400
	ds_read_b64_tr_b16 v[84:85], v153 offset:0xcc00
	s_waitcnt lgkmcnt(6)
	v_mfma_f32_32x32x16_bf16 v[34:49], v[70:73], v[86:89], v[34:49]
	ds_read_b64_tr_b16 v[86:87], v153 offset:0xd400
	ds_read_b64_tr_b16 v[88:89], v153 offset:0xdc00
	s_waitcnt lgkmcnt(6)
	v_mfma_f32_32x32x16_bf16 v[34:49], v[74:77], v[90:93], v[34:49]
	ds_read_b64_tr_b16 v[90:91], v153 offset:0xe400
	ds_read_b64_tr_b16 v[92:93], v153 offset:0xec00
	s_waitcnt lgkmcnt(6)
	v_mfma_f32_32x32x16_bf16 v[34:49], v[78:81], v[94:97], v[34:49]
	ds_read_b64_tr_b16 v[94:95], v153 offset:0xf400
	ds_read_b64_tr_b16 v[96:97], v153 offset:0xfc00
	s_waitcnt lgkmcnt(6)
	v_mfma_f32_32x32x16_bf16 v[18:33], v[66:69], v[82:85], v[18:33]
	ds_read_b64_tr_b16 v[82:83], v153 offset:0xc600
	ds_read_b64_tr_b16 v[84:85], v153 offset:0xce00
	s_waitcnt lgkmcnt(6)
	v_mfma_f32_32x32x16_bf16 v[18:33], v[70:73], v[86:89], v[18:33]
	ds_read_b64_tr_b16 v[86:87], v153 offset:0xd600
	ds_read_b64_tr_b16 v[88:89], v153 offset:0xde00
	s_waitcnt lgkmcnt(6)
	v_mfma_f32_32x32x16_bf16 v[18:33], v[74:77], v[90:93], v[18:33]
	ds_read_b64_tr_b16 v[90:91], v153 offset:0xe600
	ds_read_b64_tr_b16 v[92:93], v153 offset:0xee00
	s_waitcnt lgkmcnt(6)
	v_mfma_f32_32x32x16_bf16 v[18:33], v[78:81], v[94:97], v[18:33]
	ds_read_b64_tr_b16 v[94:95], v153 offset:0xf600
	ds_read_b64_tr_b16 v[96:97], v153 offset:0xfe00
	s_waitcnt lgkmcnt(6)
	v_mfma_f32_32x32x16_bf16 v[2:17], v[66:69], v[82:85], v[2:17]
	s_waitcnt lgkmcnt(0)
	s_barrier
	s_waitcnt lgkmcnt(4)
	v_mfma_f32_32x32x16_bf16 v[2:17], v[70:73], v[86:89], v[2:17]
	s_waitcnt lgkmcnt(2)
	v_mfma_f32_32x32x16_bf16 v[2:17], v[74:77], v[90:93], v[2:17]
	s_waitcnt lgkmcnt(0)
	v_mfma_f32_32x32x16_bf16 v[2:17], v[78:81], v[94:97], v[2:17]
